# seam: first local arriver of each XCD starts an early L2 write-back (buffer_wbl2 sc1, not waited on its arrival path); K-loop placement kept
# baseline (speedup 1.0000x reference)
.LBB0_90:
	v_readlane_b32 s4, v254, 5
	s_lshl_b32 s4, s4, 8
	v_readlane_b32 s6, v254, 3
	v_readlane_b32 s7, v254, 4
	s_add_u32 s4, s6, s4
	s_addc_u32 s5, s7, 0
	v_mov_b32_e32 v1, 0x1000
	v_mov_b32_e32 v3, 1
	global_atomic_add v3, v1, v3, s[4:5] offset:1024 sc0
	buffer_inv sc1
	v_cvt_f32_u32_e32 v1, v2
	v_sub_u32_e32 v4, 0, v2
	v_rcp_iflag_f32_e32 v1, v1
	s_nop 0
	v_mul_f32_e32 v1, 0x4f7ffffe, v1
	v_cvt_u32_f32_e32 v1, v1
	v_mul_lo_u32 v4, v4, v1
	v_mul_hi_u32 v4, v1, v4
	v_add_u32_e32 v1, v1, v4
	s_waitcnt vmcnt(1)
	v_mul_hi_u32 v1, v3, v1
	v_mul_lo_u32 v4, v1, v2
	v_sub_u32_e32 v4, v3, v4
	v_add_u32_e32 v5, 1, v1
	v_cmp_ge_u32_e32 vcc, v4, v2
	v_add_u32_e32 v3, 1, v3
	s_nop 0
	v_cndmask_b32_e32 v1, v1, v5, vcc
	v_sub_u32_e32 v5, v4, v2
	v_cndmask_b32_e32 v4, v4, v5, vcc
	v_add_u32_e32 v5, 1, v1
	v_cmp_ge_u32_e32 vcc, v4, v2
	s_nop 1
	v_cndmask_b32_e32 v1, v1, v5, vcc
	v_mul_lo_u32 v4, v2, v1
	v_add_u32_e32 v2, v4, v2
	v_cmp_ne_u32_e32 vcc, v3, v2
	v_sub_u32_e32 v5, v3, v4
	v_readfirstlane_b32 s98, v5
	s_cmp_lg_u32 s98, 1
	s_cbranch_scc1 .Lwbk_0
	buffer_wbl2 sc1
.Lwbk_0:
	s_and_saveexec_b64 s[6:7], vcc
	s_xor_b64 s[6:7], exec, s[6:7]
	s_cbranch_execz .LBB0_104
	s_waitcnt lgkmcnt(0)
	s_add_u32 s12, s28, 0x7500
	s_addc_u32 s13, s29, 0
	v_mov_b32_e32 v0, 0
	global_load_dword v0, v0, s[12:13] sc1
	s_waitcnt vmcnt(0)
	v_cmp_eq_u32_e32 vcc, v0, v1
	s_and_saveexec_b64 s[8:9], vcc
	s_cbranch_execz .LBB0_103
	s_add_u32 s10, s28, 0x4200
	s_addc_u32 s11, s29, 0
	s_mov_b32 s56, 1
	s_mov_b64 s[14:15], 0
	v_mov_b32_e32 v0, 0
	s_branch .LBB0_94

.LBB0_149:
	s_ashr_i32 s79, s78, 31
	s_lshl_b64 s[6:7], s[78:79], 11
	s_add_u32 s82, s34, s6
	s_addc_u32 s83, s35, s7
	s_and_b64 s[6:7], s[0:1], exec
	s_cselect_b32 s8, s83, s3
	s_cselect_b32 s9, s82, s2
	s_ashr_i32 s81, s80, 31
	s_lshl_b64 s[6:7], s[80:81], 11
	s_add_u32 s84, s40, s6
	s_addc_u32 s85, s41, s7
	s_and_b64 s[6:7], s[0:1], exec
	s_cselect_b32 s79, s85, s5
	s_cselect_b32 s81, s84, s4
	s_add_u32 s2, s2, 0x40080
	s_addc_u32 s3, s3, 0
	s_add_u32 s87, s4, 0x100
	v_mov_b32_e32 v0, 0
	s_addc_u32 s88, s5, 0
	s_mov_b32 s89, -2
	v_mov_b32_e32 v1, v0
	v_mov_b32_e32 v2, v0
	v_mov_b32_e32 v3, v0
	v_mov_b32_e32 v4, v0
	v_mov_b32_e32 v5, v0
	v_mov_b32_e32 v6, v0
	v_mov_b32_e32 v7, v0
	v_mov_b32_e32 v16, v0
	v_mov_b32_e32 v17, v0
	v_mov_b32_e32 v18, v0
	v_mov_b32_e32 v19, v0
	v_mov_b32_e32 v20, v0
	v_mov_b32_e32 v21, v0
	v_mov_b32_e32 v22, v0
	v_mov_b32_e32 v23, v0
	v_mov_b32_e32 v32, v0
	v_mov_b32_e32 v33, v0
	v_mov_b32_e32 v34, v0
	v_mov_b32_e32 v35, v0
	s_waitcnt vmcnt(0)
	v_mov_b64_e32 v[8:9], 0
	v_mov_b64_e32 v[10:11], 0
	v_mov_b64_e32 v[12:13], 0
	v_mov_b64_e32 v[14:15], 0
	v_mov_b64_e32 v[24:25], 0
	v_mov_b64_e32 v[26:27], 0
	v_mov_b64_e32 v[28:29], 0
	v_mov_b64_e32 v[30:31], 0
	v_mov_b64_e32 v[36:37], 0
	v_mov_b64_e32 v[38:39], 0
	v_mov_b64_e32 v[40:41], 0
	v_mov_b64_e32 v[42:43], 0
	v_mov_b64_e32 v[44:45], 0
	v_mov_b64_e32 v[46:47], 0
	v_mov_b64_e32 v[64:65], 0
	v_mov_b64_e32 v[66:67], 0
	v_mov_b64_e32 v[68:69], 0
	v_mov_b64_e32 v[70:71], 0
	v_mov_b64_e32 v[72:73], 0
	v_mov_b64_e32 v[74:75], 0
	v_mov_b64_e32 v[76:77], 0
	v_mov_b64_e32 v[78:79], 0
	v_mov_b64_e32 v[80:81], 0
	v_mov_b64_e32 v[82:83], 0
	v_mov_b64_e32 v[84:85], 0
	v_mov_b64_e32 v[86:87], 0
	v_mov_b64_e32 v[88:89], 0
	v_mov_b64_e32 v[90:91], 0
	v_mov_b64_e32 v[92:93], 0
	v_mov_b64_e32 v[94:95], 0
	v_mov_b64_e32 v[96:97], 0
	v_mov_b64_e32 v[98:99], 0
	v_mov_b64_e32 v[100:101], 0
	v_mov_b64_e32 v[102:103], 0
	v_mov_b64_e32 v[104:105], 0
	v_mov_b64_e32 v[106:107], 0
	v_mov_b64_e32 v[108:109], 0
	v_mov_b64_e32 v[110:111], 0
	v_mov_b64_e32 v[112:113], 0
	v_mov_b64_e32 v[114:115], 0
	v_mov_b64_e32 v[116:117], 0
	v_mov_b64_e32 v[118:119], 0
	v_mov_b64_e32 v[120:121], 0
	v_mov_b64_e32 v[122:123], 0
	v_mov_b64_e32 v[124:125], 0
	v_mov_b64_e32 v[126:127], 0
	v_mov_b64_e32 v[128:129], 0
	v_mov_b64_e32 v[130:131], 0
	v_mov_b64_e32 v[132:133], 0
	v_mov_b64_e32 v[134:135], 0
	v_mov_b64_e32 v[136:137], 0
	v_mov_b64_e32 v[138:139], 0
	v_mov_b64_e32 v[140:141], 0
	v_mov_b64_e32 v[142:143], 0
	s_nop 0
	s_nop 0
	s_nop 0
	s_nop 0
	s_nop 0
	s_nop 0
	s_nop 0
	s_nop 0
	s_nop 0
	s_nop 0

.Lwbk_1:
	s_and_saveexec_b64 s[6:7], vcc
	s_xor_b64 s[6:7], exec, s[6:7]
	s_cbranch_execz .LBB0_326
	s_waitcnt lgkmcnt(0)
	s_add_u32 s12, s28, 0x7500
	s_addc_u32 s13, s29, 0
	v_mov_b32_e32 v0, 0
	global_load_dword v0, v0, s[12:13] sc1
	s_waitcnt vmcnt(0)
	v_cmp_eq_u32_e32 vcc, v0, v1
	s_and_saveexec_b64 s[8:9], vcc
	s_cbranch_execz .LBB0_325
	s_add_u32 s10, s28, 0x4200
	s_addc_u32 s11, s29, 0
	s_mov_b32 s40, 1
	s_mov_b64 s[14:15], 0
	v_mov_b32_e32 v0, 0
	s_branch .LBB0_316

.LBB0_740:
	s_ashr_i32 s11, s10, 31
	v_cmp_lt_i64_e32 vcc, s[14:15], v[164:165]
	s_lshl_b64 s[14:15], s[10:11], 11
	s_add_u32 s14, s41, s14
	s_addc_u32 s15, s54, s15
	s_and_b64 s[18:19], vcc, exec
	s_cselect_b32 s6, s15, s53
	s_cselect_b32 s11, s14, s52
	s_ashr_i32 s13, s12, 31
	s_lshl_b64 s[18:19], s[12:13], 11
	s_add_u32 s18, s55, s18
	s_addc_u32 s19, s56, s19
	s_and_b64 s[60:61], vcc, exec
	s_cselect_b32 s13, s19, s59
	s_cselect_b32 s80, s18, s58
	s_add_u32 s52, s52, 0x40080
	s_addc_u32 s53, s53, 0
	s_add_u32 s81, s58, 0x100
	v_mov_b32_e32 v0, 0
	s_addc_u32 s82, s59, 0
	s_mov_b32 s83, -2
	s_waitcnt lgkmcnt(0)
	v_mov_b32_e32 v1, v0
	v_mov_b32_e32 v2, v0
	v_mov_b32_e32 v3, v0
	v_mov_b32_e32 v4, v0
	v_mov_b32_e32 v5, v0
	v_mov_b32_e32 v6, v0
	v_mov_b32_e32 v7, v0
	v_mov_b32_e32 v16, v0
	v_mov_b32_e32 v17, v0
	v_mov_b32_e32 v18, v0
	v_mov_b32_e32 v19, v0
	v_mov_b32_e32 v20, v0
	v_mov_b32_e32 v21, v0
	v_mov_b32_e32 v22, v0
	v_mov_b32_e32 v23, v0
	v_mov_b32_e32 v32, v0
	v_mov_b32_e32 v33, v0
	v_mov_b32_e32 v34, v0
	v_mov_b32_e32 v35, v0
	s_waitcnt vmcnt(0)
	v_mov_b64_e32 v[8:9], 0
	v_mov_b64_e32 v[10:11], 0
	v_mov_b64_e32 v[12:13], 0
	v_mov_b64_e32 v[14:15], 0
	v_mov_b64_e32 v[24:25], 0
	v_mov_b64_e32 v[26:27], 0
	v_mov_b64_e32 v[28:29], 0
	v_mov_b64_e32 v[30:31], 0
	v_mov_b64_e32 v[36:37], 0
	v_mov_b64_e32 v[38:39], 0
	v_mov_b64_e32 v[40:41], 0
	v_mov_b64_e32 v[42:43], 0
	v_mov_b64_e32 v[44:45], 0
	v_mov_b64_e32 v[46:47], 0
	v_mov_b64_e32 v[48:49], 0
	v_mov_b64_e32 v[50:51], 0
	v_mov_b64_e32 v[52:53], 0
	v_mov_b64_e32 v[54:55], 0
	v_mov_b64_e32 v[56:57], 0
	v_mov_b64_e32 v[58:59], 0
	v_mov_b64_e32 v[60:61], 0
	v_mov_b64_e32 v[62:63], 0
	v_mov_b64_e32 v[64:65], 0
	v_mov_b64_e32 v[66:67], 0
	v_mov_b64_e32 v[68:69], 0
	v_mov_b64_e32 v[70:71], 0
	v_mov_b64_e32 v[72:73], 0
	v_mov_b64_e32 v[74:75], 0
	v_mov_b64_e32 v[76:77], 0
	v_mov_b64_e32 v[78:79], 0
	v_mov_b64_e32 v[80:81], 0
	v_mov_b64_e32 v[82:83], 0
	v_mov_b64_e32 v[84:85], 0
	v_mov_b64_e32 v[86:87], 0
	v_mov_b64_e32 v[88:89], 0
	v_mov_b64_e32 v[90:91], 0
	v_mov_b64_e32 v[92:93], 0
	v_mov_b64_e32 v[94:95], 0
	v_mov_b64_e32 v[96:97], 0
	v_mov_b64_e32 v[98:99], 0
	v_mov_b64_e32 v[100:101], 0
	v_mov_b64_e32 v[102:103], 0
	v_mov_b64_e32 v[104:105], 0
	v_mov_b64_e32 v[106:107], 0
	v_mov_b64_e32 v[108:109], 0
	v_mov_b64_e32 v[110:111], 0
	v_mov_b64_e32 v[112:113], 0
	v_mov_b64_e32 v[114:115], 0
	v_mov_b64_e32 v[116:117], 0
	v_mov_b64_e32 v[118:119], 0
	v_mov_b64_e32 v[120:121], 0
	v_mov_b64_e32 v[122:123], 0
	v_mov_b64_e32 v[124:125], 0
	v_mov_b64_e32 v[126:127], 0
	s_nop 0
	s_nop 0
	s_nop 0
	s_nop 0
	s_nop 0
	s_nop 0
	s_nop 0
	s_nop 0
	s_nop 0
	s_nop 0
	s_nop 0
	s_nop 0
	s_nop 0
	s_nop 0

.LBB0_874:
	s_ashr_i32 s61, s60, 31
	s_lshl_b64 s[66:67], s[60:61], 11
	s_add_u32 s66, s34, s66
	s_addc_u32 s67, s35, s67
	s_and_b64 s[68:69], s[62:63], exec
	s_cselect_b32 s3, s67, s85
	s_cselect_b32 s61, s66, s84
	s_ashr_i32 s65, s64, 31
	s_lshl_b64 s[68:69], s[64:65], 11
	s_add_u32 s78, s19, s68
	s_addc_u32 s79, s40, s69
	s_and_b64 s[68:69], s[62:63], exec
	s_cselect_b32 s65, s79, s87
	s_cselect_b32 s73, s78, s86
	s_cmp_lg_u32 s4, 0
	s_cselect_b64 s[82:83], -1, 0
	s_add_u32 s69, s86, 0x100
	s_addc_u32 s71, s87, 0
	s_cmp_eq_u32 s4, 0
	s_cbranch_scc1 .LBB0_878
	s_add_u32 s4, s84, 0x100
	s_addc_u32 s5, s85, 0
	s_add_u32 s86, s86, 0x80080
	v_mov_b32_e32 v0, 0
	s_addc_u32 s87, s87, 0
	s_mov_b32 s68, -2
	v_mov_b32_e32 v1, v0
	v_mov_b32_e32 v2, v0
	v_mov_b32_e32 v3, v0
	v_mov_b32_e32 v4, v0
	v_mov_b32_e32 v5, v0
	v_mov_b32_e32 v6, v0
	v_mov_b32_e32 v7, v0
	v_mov_b32_e32 v8, v0
	v_mov_b32_e32 v9, v0
	v_mov_b32_e32 v10, v0
	v_mov_b32_e32 v11, v0
	v_mov_b32_e32 v12, v0
	v_mov_b32_e32 v13, v0
	v_mov_b32_e32 v14, v0
	v_mov_b32_e32 v15, v0
	v_mov_b32_e32 v16, v0
	v_mov_b32_e32 v17, v0
	v_mov_b32_e32 v18, v0
	v_mov_b32_e32 v19, v0
	v_mov_b32_e32 v20, v0
	v_mov_b32_e32 v21, v0
	v_mov_b32_e32 v22, v0
	v_mov_b32_e32 v23, v0
	v_mov_b32_e32 v24, v0
	v_mov_b32_e32 v25, v0
	v_mov_b32_e32 v26, v0
	v_mov_b32_e32 v27, v0
	v_mov_b32_e32 v28, v0
	v_mov_b32_e32 v29, v0
	v_mov_b32_e32 v30, v0
	v_mov_b32_e32 v31, v0
	v_mov_b32_e32 v32, v0
	v_mov_b32_e32 v33, v0
	v_mov_b32_e32 v34, v0
	v_mov_b32_e32 v35, v0
	s_waitcnt vmcnt(0)
	v_mov_b64_e32 v[36:37], 0
	v_mov_b64_e32 v[38:39], 0
	v_mov_b64_e32 v[40:41], 0
	v_mov_b64_e32 v[42:43], 0
	v_mov_b64_e32 v[44:45], 0
	v_mov_b64_e32 v[46:47], 0
	v_mov_b64_e32 v[48:49], 0
	v_mov_b64_e32 v[50:51], 0
	v_mov_b64_e32 v[52:53], 0
	v_mov_b64_e32 v[54:55], 0
	v_mov_b64_e32 v[56:57], 0
	v_mov_b64_e32 v[58:59], 0
	v_mov_b64_e32 v[60:61], 0
	v_mov_b64_e32 v[62:63], 0
	v_mov_b64_e32 v[64:65], 0
	v_mov_b64_e32 v[66:67], 0
	v_mov_b64_e32 v[68:69], 0
	v_mov_b64_e32 v[70:71], 0
	v_mov_b64_e32 v[72:73], 0
	v_mov_b64_e32 v[74:75], 0
	v_mov_b64_e32 v[76:77], 0
	v_mov_b64_e32 v[78:79], 0
	v_mov_b64_e32 v[80:81], 0
	v_mov_b64_e32 v[82:83], 0
	v_mov_b64_e32 v[84:85], 0
	v_mov_b64_e32 v[86:87], 0
	v_mov_b64_e32 v[88:89], 0
	v_mov_b64_e32 v[90:91], 0
	v_mov_b64_e32 v[92:93], 0
	v_mov_b64_e32 v[94:95], 0
	s_nop 0
	s_nop 0
	s_nop 0
	s_nop 0
	s_nop 0
	s_nop 0
	s_nop 0
	s_nop 0
	s_nop 0
	s_nop 0

.LBB0_970:
	s_ashr_i32 s65, s64, 31
	s_lshl_b64 s[78:79], s[64:65], 11
	s_add_u32 s78, s34, s78
	s_addc_u32 s79, s35, s79
	s_and_b64 s[80:81], s[2:3], exec
	s_cselect_b32 s65, s79, s5
	s_cselect_b32 s73, s78, s4
	s_ashr_i32 s67, s66, 31
	s_lshl_b64 s[80:81], s[66:67], 11
	s_add_u32 s80, s40, s80
	s_addc_u32 s81, s41, s81
	s_and_b64 s[82:83], s[2:3], exec
	s_cselect_b32 s67, s81, s7
	s_cselect_b32 s76, s80, s6
	s_add_u32 s4, s4, 0x40080
	s_addc_u32 s5, s5, 0
	s_add_u32 s86, s6, 0x100
	v_mov_b32_e32 v0, 0
	s_addc_u32 s87, s7, 0
	s_mov_b32 s88, -2
	v_mov_b32_e32 v1, 0
	v_mov_b64_e32 v[2:3], 0
	v_mov_b64_e32 v[4:5], 0
	v_mov_b64_e32 v[6:7], 0
	v_mov_b64_e32 v[8:9], 0
	v_mov_b64_e32 v[10:11], 0
	v_mov_b64_e32 v[12:13], 0
	v_mov_b64_e32 v[14:15], 0
	v_mov_b64_e32 v[16:17], 0
	v_mov_b64_e32 v[18:19], 0
	v_mov_b64_e32 v[20:21], 0
	v_mov_b64_e32 v[22:23], 0
	v_mov_b64_e32 v[24:25], 0
	v_mov_b64_e32 v[26:27], 0
	v_mov_b64_e32 v[28:29], 0
	v_mov_b64_e32 v[30:31], 0
	v_mov_b64_e32 v[32:33], 0
	v_mov_b64_e32 v[34:35], 0
	v_mov_b64_e32 v[36:37], 0
	v_mov_b64_e32 v[38:39], 0
	v_mov_b64_e32 v[40:41], 0
	v_mov_b64_e32 v[42:43], 0
	v_mov_b64_e32 v[44:45], 0
	v_mov_b64_e32 v[46:47], 0
	v_mov_b64_e32 v[48:49], 0
	v_mov_b64_e32 v[50:51], 0
	v_mov_b64_e32 v[52:53], 0
	v_mov_b64_e32 v[54:55], 0
	v_mov_b64_e32 v[56:57], 0
	v_mov_b64_e32 v[58:59], 0
	v_mov_b64_e32 v[60:61], 0
	v_mov_b64_e32 v[62:63], 0
	v_mov_b64_e32 v[64:65], 0
	v_mov_b64_e32 v[66:67], 0
	v_mov_b64_e32 v[68:69], 0
	v_mov_b64_e32 v[70:71], 0
	v_mov_b64_e32 v[72:73], 0
	v_mov_b64_e32 v[74:75], 0
	v_mov_b64_e32 v[76:77], 0
	v_mov_b64_e32 v[78:79], 0
	v_mov_b64_e32 v[80:81], 0
	v_mov_b64_e32 v[82:83], 0
	v_mov_b64_e32 v[84:85], 0
	v_mov_b64_e32 v[86:87], 0
	v_mov_b64_e32 v[88:89], 0
	v_mov_b64_e32 v[90:91], 0
	v_mov_b64_e32 v[92:93], 0
	v_mov_b64_e32 v[94:95], 0
	v_mov_b64_e32 v[96:97], 0
	v_mov_b64_e32 v[98:99], 0
	v_mov_b64_e32 v[100:101], 0
	v_mov_b64_e32 v[102:103], 0
	v_mov_b64_e32 v[104:105], 0
	v_mov_b64_e32 v[106:107], 0
	v_mov_b64_e32 v[108:109], 0
	v_mov_b64_e32 v[110:111], 0
	v_mov_b64_e32 v[112:113], 0
	v_mov_b64_e32 v[114:115], 0
	v_mov_b64_e32 v[116:117], 0
	v_mov_b64_e32 v[118:119], 0
	v_mov_b64_e32 v[124:125], 0
	v_mov_b64_e32 v[126:127], 0
	v_mov_b64_e32 v[132:133], 0
	v_mov_b64_e32 v[134:135], 0
	s_nop 0
	s_nop 0
	s_nop 0
	s_nop 0
	s_nop 0
	s_nop 0
	s_nop 0
	s_nop 0
	s_nop 0
	s_nop 0

.LBB0_1079:
	s_add_u32 s73, s38, 0x100
	v_mov_b32_e32 v0, 0
	s_addc_u32 s76, s39, 0
	s_mov_b32 s77, -2
	s_waitcnt lgkmcnt(0)
	v_mov_b32_e32 v1, 0
	v_mov_b64_e32 v[2:3], 0
	v_mov_b64_e32 v[4:5], 0
	v_mov_b64_e32 v[6:7], 0
	v_mov_b64_e32 v[8:9], 0
	v_mov_b64_e32 v[10:11], 0
	v_mov_b64_e32 v[12:13], 0
	v_mov_b64_e32 v[14:15], 0
	v_mov_b64_e32 v[16:17], 0
	v_mov_b64_e32 v[18:19], 0
	v_mov_b64_e32 v[20:21], 0
	v_mov_b64_e32 v[22:23], 0
	v_mov_b64_e32 v[24:25], 0
	v_mov_b64_e32 v[26:27], 0
	v_mov_b64_e32 v[28:29], 0
	v_mov_b64_e32 v[30:31], 0
	v_mov_b64_e32 v[32:33], 0
	v_mov_b64_e32 v[34:35], 0
	v_mov_b64_e32 v[36:37], 0
	v_mov_b64_e32 v[38:39], 0
	v_mov_b64_e32 v[40:41], 0
	v_mov_b64_e32 v[42:43], 0
	v_mov_b64_e32 v[44:45], 0
	v_mov_b64_e32 v[46:47], 0
	v_mov_b64_e32 v[48:49], 0
	v_mov_b64_e32 v[50:51], 0
	v_mov_b64_e32 v[52:53], 0
	v_mov_b64_e32 v[54:55], 0
	v_mov_b64_e32 v[56:57], 0
	v_mov_b64_e32 v[58:59], 0
	v_mov_b64_e32 v[60:61], 0
	v_mov_b64_e32 v[62:63], 0
	v_mov_b64_e32 v[64:65], 0
	v_mov_b64_e32 v[66:67], 0
	v_mov_b64_e32 v[68:69], 0
	v_mov_b64_e32 v[70:71], 0
	v_mov_b64_e32 v[72:73], 0
	v_mov_b64_e32 v[74:75], 0
	v_mov_b64_e32 v[76:77], 0
	v_mov_b64_e32 v[78:79], 0
	v_mov_b64_e32 v[80:81], 0
	v_mov_b64_e32 v[82:83], 0
	v_mov_b64_e32 v[84:85], 0
	v_mov_b64_e32 v[86:87], 0
	v_mov_b64_e32 v[88:89], 0
	v_mov_b64_e32 v[90:91], 0
	v_mov_b64_e32 v[92:93], 0
	v_mov_b64_e32 v[94:95], 0
	v_mov_b64_e32 v[96:97], 0
	v_mov_b64_e32 v[98:99], 0
	v_mov_b64_e32 v[100:101], 0
	v_mov_b64_e32 v[102:103], 0
	v_mov_b64_e32 v[104:105], 0
	v_mov_b64_e32 v[106:107], 0
	v_mov_b64_e32 v[108:109], 0
	v_mov_b64_e32 v[110:111], 0
	v_mov_b64_e32 v[112:113], 0
	v_mov_b64_e32 v[114:115], 0
	v_mov_b64_e32 v[116:117], 0
	v_mov_b64_e32 v[118:119], 0
	v_mov_b64_e32 v[120:121], 0
	v_mov_b64_e32 v[122:123], 0
	v_mov_b64_e32 v[124:125], 0
	v_mov_b64_e32 v[126:127], 0
	s_nop 0
	s_nop 0
	s_nop 0
	s_nop 0
	s_nop 0
	s_nop 0
	s_nop 0
	s_nop 0
	s_nop 0
	s_nop 0

.Lwbk_7:
	s_and_saveexec_b64 s[6:7], vcc
	s_xor_b64 s[6:7], exec, s[6:7]
	s_cbranch_execz .LBB0_1131
	s_waitcnt lgkmcnt(0)
	s_add_u32 s14, s28, 0x7500
	s_addc_u32 s15, s29, 0
	v_mov_b32_e32 v0, 0
	global_load_dword v0, v0, s[14:15] sc1
	s_waitcnt vmcnt(0)
	v_cmp_eq_u32_e32 vcc, v0, v1
	s_and_saveexec_b64 s[10:11], vcc
	s_cbranch_execz .LBB0_1130
	s_add_u32 s12, s28, 0x4200
	s_addc_u32 s13, s29, 0
	s_mov_b32 s40, 1
	s_mov_b64 s[18:19], 0
	v_mov_b32_e32 v0, 0
	s_branch .LBB0_1121

.LBB0_1529:
	s_ashr_i32 s11, s10, 31
	v_cmp_lt_i64_e32 vcc, s[14:15], v[164:165]
	s_lshl_b64 s[14:15], s[10:11], 11
	s_add_u32 s14, s41, s14
	s_addc_u32 s15, s42, s15
	s_and_b64 s[18:19], vcc, exec
	s_cselect_b32 s11, s15, s25
	s_cselect_b32 s61, s14, s24
	s_ashr_i32 s13, s12, 31
	s_lshl_b64 s[18:19], s[12:13], 11
	s_add_u32 s18, s43, s18
	s_addc_u32 s19, s44, s19
	s_and_b64 s[38:39], vcc, exec
	s_cselect_b32 s13, s19, s37
	s_cselect_b32 s62, s18, s36
	s_add_u32 s24, s24, 0x40080
	s_addc_u32 s25, s25, 0
	s_add_u32 s63, s36, 0x100
	v_mov_b32_e32 v0, 0
	s_addc_u32 s64, s37, 0
	s_mov_b32 s65, -2
	s_waitcnt lgkmcnt(0)
	v_mov_b32_e32 v1, v0
	v_mov_b32_e32 v2, v0
	v_mov_b32_e32 v3, v0
	v_mov_b32_e32 v4, v0
	v_mov_b32_e32 v5, v0
	v_mov_b32_e32 v6, v0
	v_mov_b32_e32 v7, v0
	v_mov_b32_e32 v16, v0
	v_mov_b32_e32 v17, v0
	v_mov_b32_e32 v18, v0
	v_mov_b32_e32 v19, v0
	v_mov_b32_e32 v20, v0
	v_mov_b32_e32 v21, v0
	v_mov_b32_e32 v22, v0
	v_mov_b32_e32 v23, v0
	v_mov_b32_e32 v32, v0
	v_mov_b32_e32 v33, v0
	v_mov_b32_e32 v34, v0
	v_mov_b32_e32 v35, v0
	s_waitcnt vmcnt(0)
	v_mov_b64_e32 v[8:9], 0
	v_mov_b64_e32 v[10:11], 0
	v_mov_b64_e32 v[12:13], 0
	v_mov_b64_e32 v[14:15], 0
	v_mov_b64_e32 v[24:25], 0
	v_mov_b64_e32 v[26:27], 0
	v_mov_b64_e32 v[28:29], 0
	v_mov_b64_e32 v[30:31], 0
	v_mov_b64_e32 v[36:37], 0
	v_mov_b64_e32 v[38:39], 0
	v_mov_b64_e32 v[40:41], 0
	v_mov_b64_e32 v[42:43], 0
	v_mov_b64_e32 v[44:45], 0
	v_mov_b64_e32 v[46:47], 0
	v_mov_b64_e32 v[48:49], 0
	v_mov_b64_e32 v[50:51], 0
	v_mov_b64_e32 v[52:53], 0
	v_mov_b64_e32 v[54:55], 0
	v_mov_b64_e32 v[56:57], 0
	v_mov_b64_e32 v[58:59], 0
	v_mov_b64_e32 v[60:61], 0
	v_mov_b64_e32 v[62:63], 0
	v_mov_b64_e32 v[64:65], 0
	v_mov_b64_e32 v[66:67], 0
	v_mov_b64_e32 v[68:69], 0
	v_mov_b64_e32 v[70:71], 0
	v_mov_b64_e32 v[72:73], 0
	v_mov_b64_e32 v[74:75], 0
	v_mov_b64_e32 v[76:77], 0
	v_mov_b64_e32 v[78:79], 0
	v_mov_b64_e32 v[80:81], 0
	v_mov_b64_e32 v[82:83], 0
	v_mov_b64_e32 v[84:85], 0
	v_mov_b64_e32 v[86:87], 0
	v_mov_b64_e32 v[88:89], 0
	v_mov_b64_e32 v[90:91], 0
	v_mov_b64_e32 v[92:93], 0
	v_mov_b64_e32 v[94:95], 0
	v_mov_b64_e32 v[96:97], 0
	v_mov_b64_e32 v[98:99], 0
	v_mov_b64_e32 v[100:101], 0
	v_mov_b64_e32 v[102:103], 0
	v_mov_b64_e32 v[104:105], 0
	v_mov_b64_e32 v[106:107], 0
	v_mov_b64_e32 v[108:109], 0
	v_mov_b64_e32 v[110:111], 0
	v_mov_b64_e32 v[112:113], 0
	v_mov_b64_e32 v[114:115], 0
	v_mov_b64_e32 v[116:117], 0
	v_mov_b64_e32 v[118:119], 0
	v_mov_b64_e32 v[120:121], 0
	v_mov_b64_e32 v[122:123], 0
	v_mov_b64_e32 v[124:125], 0
	v_mov_b64_e32 v[126:127], 0
	s_nop 0
	s_nop 0
	s_nop 0
	s_nop 0
	s_nop 0
	s_nop 0
	s_nop 0
	s_nop 0

.LBB0_1656:
	s_ashr_i32 s39, s38, 31
	s_lshl_b64 s[6:7], s[38:39], 11
	s_add_u32 s44, s34, s6
	s_addc_u32 s45, s35, s7
	s_and_b64 s[6:7], s[40:41], exec
	s_cselect_b32 s3, s45, s49
	s_cselect_b32 s5, s44, s48
	s_ashr_i32 s43, s42, 31
	s_lshl_b64 s[6:7], s[42:43], 11
	s_add_u32 s46, s37, s6
	s_addc_u32 s47, s52, s7
	s_and_b64 s[6:7], s[40:41], exec
	s_cselect_b32 s39, s47, s51
	s_cselect_b32 s43, s46, s50
	s_cmp_lg_u32 s54, 0
	s_cselect_b64 s[6:7], -1, 0
	s_add_u32 s85, s50, 0x100
	s_addc_u32 s86, s51, 0
	s_cmp_eq_u32 s54, 0
	s_cbranch_scc1 .LBB0_1660
	s_add_u32 s56, s48, 0x100
	s_addc_u32 s57, s49, 0
	s_add_u32 s50, s50, 0x80080
	v_mov_b32_e32 v0, 0
	s_addc_u32 s51, s51, 0
	s_mov_b32 s58, -2
	v_mov_b32_e32 v1, 0
	v_mov_b64_e32 v[2:3], 0
	v_mov_b64_e32 v[4:5], 0
	v_mov_b64_e32 v[6:7], 0
	v_mov_b64_e32 v[8:9], 0
	v_mov_b64_e32 v[10:11], 0
	v_mov_b64_e32 v[12:13], 0
	v_mov_b64_e32 v[14:15], 0
	v_mov_b64_e32 v[16:17], 0
	v_mov_b64_e32 v[18:19], 0
	v_mov_b64_e32 v[20:21], 0
	v_mov_b64_e32 v[22:23], 0
	v_mov_b64_e32 v[24:25], 0
	v_mov_b64_e32 v[26:27], 0
	v_mov_b64_e32 v[28:29], 0
	v_mov_b64_e32 v[30:31], 0
	v_mov_b64_e32 v[32:33], 0
	v_mov_b64_e32 v[34:35], 0
	v_mov_b64_e32 v[36:37], 0
	v_mov_b64_e32 v[38:39], 0
	v_mov_b64_e32 v[40:41], 0
	v_mov_b64_e32 v[42:43], 0
	v_mov_b64_e32 v[44:45], 0
	v_mov_b64_e32 v[46:47], 0
	v_mov_b64_e32 v[48:49], 0
	v_mov_b64_e32 v[50:51], 0
	v_mov_b64_e32 v[52:53], 0
	v_mov_b64_e32 v[54:55], 0
	v_mov_b64_e32 v[56:57], 0
	v_mov_b64_e32 v[58:59], 0
	v_mov_b64_e32 v[60:61], 0
	v_mov_b64_e32 v[62:63], 0
	v_mov_b64_e32 v[64:65], 0
	v_mov_b64_e32 v[66:67], 0
	v_mov_b64_e32 v[68:69], 0
	v_mov_b64_e32 v[70:71], 0
	v_mov_b64_e32 v[72:73], 0
	v_mov_b64_e32 v[74:75], 0
	v_mov_b64_e32 v[76:77], 0
	v_mov_b64_e32 v[78:79], 0
	v_mov_b64_e32 v[80:81], 0
	v_mov_b64_e32 v[82:83], 0
	v_mov_b64_e32 v[84:85], 0
	v_mov_b64_e32 v[86:87], 0
	v_mov_b64_e32 v[88:89], 0
	v_mov_b64_e32 v[90:91], 0
	v_mov_b64_e32 v[92:93], 0
	v_mov_b64_e32 v[94:95], 0
	s_nop 0
	s_nop 0
	s_nop 0
	s_nop 0
	s_nop 0
	s_nop 0
	s_nop 0
	s_nop 0
	s_nop 0
	s_nop 0

.Lwbk_14:
	s_and_saveexec_b64 s[6:7], vcc
	s_xor_b64 s[6:7], exec, s[6:7]
	s_cbranch_execz .LBB0_1839
	s_waitcnt lgkmcnt(0)
	s_add_u32 s12, s28, 0x7500
	s_addc_u32 s13, s29, 0
	v_mov_b32_e32 v0, 0
	global_load_dword v0, v0, s[12:13] sc1
	s_waitcnt vmcnt(0)
	v_cmp_eq_u32_e32 vcc, v0, v1
	s_and_saveexec_b64 s[8:9], vcc
	s_cbranch_execz .LBB0_1838
	s_add_u32 s10, s28, 0x4200
	s_addc_u32 s11, s29, 0
	s_mov_b32 s31, 1
	s_mov_b64 s[14:15], 0
	v_mov_b32_e32 v0, 0
	s_branch .LBB0_1829

.LBB0_1881:
	s_add_u32 s56, s24, 0x100
	v_mov_b32_e32 v0, 0
	s_addc_u32 s57, s25, 0
	s_mov_b32 s58, -2
	v_mov_b32_e32 v1, v0
	v_mov_b32_e32 v2, v0
	v_mov_b32_e32 v3, v0
	v_mov_b32_e32 v4, v0
	v_mov_b32_e32 v5, v0
	v_mov_b32_e32 v6, v0
	v_mov_b32_e32 v7, v0
	v_mov_b32_e32 v16, v0
	v_mov_b32_e32 v17, v0
	v_mov_b32_e32 v18, v0
	v_mov_b32_e32 v19, v0
	v_mov_b32_e32 v20, v0
	v_mov_b32_e32 v21, v0
	v_mov_b32_e32 v22, v0
	v_mov_b32_e32 v23, v0
	v_mov_b32_e32 v32, v0
	v_mov_b32_e32 v33, v0
	v_mov_b32_e32 v34, v0
	v_mov_b32_e32 v35, v0
	s_waitcnt vmcnt(0)
	v_mov_b64_e32 v[8:9], 0
	v_mov_b64_e32 v[10:11], 0
	v_mov_b64_e32 v[12:13], 0
	v_mov_b64_e32 v[14:15], 0
	v_mov_b64_e32 v[24:25], 0
	v_mov_b64_e32 v[26:27], 0
	v_mov_b64_e32 v[28:29], 0
	v_mov_b64_e32 v[30:31], 0
	v_mov_b64_e32 v[36:37], 0
	v_mov_b64_e32 v[38:39], 0
	v_mov_b64_e32 v[40:41], 0
	v_mov_b64_e32 v[42:43], 0
	v_mov_b64_e32 v[44:45], 0
	v_mov_b64_e32 v[46:47], 0
	v_mov_b64_e32 v[48:49], 0
	v_mov_b64_e32 v[50:51], 0
	v_mov_b64_e32 v[52:53], 0
	v_mov_b64_e32 v[54:55], 0
	v_mov_b64_e32 v[56:57], 0
	v_mov_b64_e32 v[58:59], 0
	v_mov_b64_e32 v[60:61], 0
	v_mov_b64_e32 v[62:63], 0
	v_mov_b64_e32 v[64:65], 0
	v_mov_b64_e32 v[66:67], 0
	v_mov_b64_e32 v[68:69], 0
	v_mov_b64_e32 v[70:71], 0
	v_mov_b64_e32 v[72:73], 0
	v_mov_b64_e32 v[74:75], 0
	v_mov_b64_e32 v[76:77], 0
	v_mov_b64_e32 v[78:79], 0
	v_mov_b64_e32 v[80:81], 0
	v_mov_b64_e32 v[82:83], 0
	v_mov_b64_e32 v[84:85], 0
	v_mov_b64_e32 v[86:87], 0
	v_mov_b64_e32 v[88:89], 0
	v_mov_b64_e32 v[90:91], 0
	v_mov_b64_e32 v[92:93], 0
	v_mov_b64_e32 v[94:95], 0
	v_mov_b64_e32 v[96:97], 0
	v_mov_b64_e32 v[98:99], 0
	v_mov_b64_e32 v[100:101], 0
	v_mov_b64_e32 v[102:103], 0
	v_mov_b64_e32 v[104:105], 0
	v_mov_b64_e32 v[106:107], 0
	v_mov_b64_e32 v[108:109], 0
	v_mov_b64_e32 v[110:111], 0
	v_mov_b64_e32 v[112:113], 0
	v_mov_b64_e32 v[114:115], 0
	v_mov_b64_e32 v[116:117], 0
	v_mov_b64_e32 v[118:119], 0
	v_mov_b64_e32 v[120:121], 0
	v_mov_b64_e32 v[122:123], 0
	v_mov_b64_e32 v[124:125], 0
	v_mov_b64_e32 v[126:127], 0
	s_nop 0
	s_nop 0
	s_nop 0
	s_nop 0
	s_nop 0
	s_nop 0
	s_nop 0
	s_nop 0
	s_nop 0
	s_nop 0
